# v63 + in-proj K-loop: next-tile loads use SGPR tile base + constant 32-bit lane offsets (SADDR form), 14 address VALU per K-step replaced by 8 SALU
# baseline (speedup 1.0000x reference)
; #define G_LOAD(KT) do { const int k0_ = (KT) << 6; _Pragma("unroll") for (int p = 0; p < 4; ++p) { \
;     ra[p] = *(const u32x4*)(ap + (size_t)(64 * p) * lda + k0_); rb[p] = *(const u32x4*)(bp + (size_t)(64 * p) * ldb + k0_); } } while (0)
; template <bool SWAP, bool SSQ, bool ZERO = true>
; DI void gemm_main(const u16* __restrict__ A, int lda, const u16* __restrict__ Bt, int ldb, int K, char* lds,
;                   f32x16 (&acc)[4][2], float* rs_lds) {
;     ...
;   if (ZERO) {
; #pragma unroll
;     for (int mt = 0; mt < 4; ++mt)
; #pragma unroll
;       for (int nt = 0; nt < 2; ++nt)
; #pragma unroll
;         for (int i = 0; i < 16; ++i) acc[mt][nt][i] = 0.f;
;   }
;   const int nk = K >> 6;
;   char* const wbase = lds + lr * GS + lc * 16;
;   const char* abase = lds + (wm * 128 + r) * GS + hf * 16;
;   const char* bbase = lds + G_TILE + (wn * 64 + r) * GS + hf * 16;
;     ...
;   G_LOAD(0);
;   __syncthreads();
;   G_WRITE(0);
;   G_LOAD(1);
;   __syncthreads();
.Lxss_done_a:
	s_or_b64 exec, exec, s[100:101]
	s_waitcnt lgkmcnt(0)
	s_barrier
	v_mad_u64_u32 v[164:165], s[62:63], v35, s9, v[42:43]
	v_mad_u32_u24 v163, v43, s9, v42
	s_mov_b64 s[86:87], 0
	s_mov_b32 s53, 2
	s_waitcnt vmcnt(7)
	ds_write_b128 v162, v[2:5]
	s_waitcnt vmcnt(6)
	ds_write_b128 v162, v[6:9] offset:36864
	s_waitcnt vmcnt(5)
	ds_write_b128 v162, v[10:13] offset:9216
	s_waitcnt vmcnt(4)
	ds_write_b128 v162, v[14:17] offset:46080
	s_waitcnt vmcnt(3)
	ds_write_b128 v162, v[18:21] offset:18432
	s_waitcnt vmcnt(2)
	ds_write_b128 v162, v[22:25] offset:55296
	s_waitcnt vmcnt(1)
	ds_write_b128 v162, v[26:29] offset:27648
	s_waitcnt vmcnt(0)
	ds_write_b128 v162, v[30:33] offset:64512
	global_load_dwordx4 v[130:133], v[38:39], off offset:128
	global_load_dwordx4 v[134:137], v[40:41], off offset:128
	global_load_dwordx4 v[138:141], v[44:45], off offset:128
	global_load_dwordx4 v[142:145], v[46:47], off offset:128
	global_load_dwordx4 v[146:149], v[48:49], off offset:128
	global_load_dwordx4 v[150:153], v[50:51], off offset:128
	global_load_dwordx4 v[154:157], v[52:53], off offset:128
	global_load_dwordx4 v[158:161], v[54:55], off offset:128
	v_lshl_add_u64 v[2:3], s[0:1], 0, v[36:37]
	v_lshl_add_u64 v[2:3], v[2:3], 0, v[0:1]
	v_lshl_add_u64 v[166:167], s[14:15], 0, v[2:3]
	v_lshl_add_u64 v[2:3], s[4:5], 0, v[36:37]
	v_lshl_add_u64 v[2:3], v[2:3], 0, v[0:1]
	v_lshl_add_u64 v[168:169], s[40:41], 0, v[2:3]
	v_add_u32_e32 v220, v36, v0
	v_add_u32_e32 v221, 0x40000, v220
	v_add_u32_e32 v234, 0x80000, v220
	v_add_u32_e32 v235, 0xc0000, v220
	v_mov_b32_e32 v2, 0
	v_mov_b32_e32 v3, v2
	v_mov_b32_e32 v4, v2
	v_mov_b32_e32 v5, v2
	v_mov_b32_e32 v6, v2
	v_mov_b32_e32 v7, v2
	v_mov_b32_e32 v8, v2
	v_mov_b32_e32 v9, v2
	v_mov_b32_e32 v10, v2
	v_mov_b32_e32 v11, v2
	v_mov_b32_e32 v12, v2
	v_mov_b32_e32 v13, v2
	v_mov_b32_e32 v14, v2
	v_mov_b32_e32 v15, v2
	v_mov_b32_e32 v16, v2
	v_mov_b32_e32 v17, v2
	v_mov_b32_e32 v18, v2
	v_mov_b32_e32 v19, v2
	v_mov_b32_e32 v20, v2
	v_mov_b32_e32 v21, v2
	v_mov_b32_e32 v22, v2
	v_mov_b32_e32 v23, v2
	v_mov_b32_e32 v24, v2
	v_mov_b32_e32 v25, v2
	v_mov_b32_e32 v26, v2
	v_mov_b32_e32 v27, v2
	v_mov_b32_e32 v28, v2
	v_mov_b32_e32 v29, v2
	v_mov_b32_e32 v30, v2
	v_mov_b32_e32 v31, v2
	v_mov_b32_e32 v32, v2
	v_mov_b32_e32 v33, v2
	v_mov_b32_e32 v34, v2
	v_mov_b32_e32 v35, v2
	v_mov_b32_e32 v36, v2
	v_mov_b32_e32 v37, v2
	v_mov_b32_e32 v38, v2
	v_mov_b32_e32 v39, v2
	v_mov_b32_e32 v40, v2
	v_mov_b32_e32 v41, v2
	v_mov_b32_e32 v42, v2
	v_mov_b32_e32 v43, v2
	v_mov_b32_e32 v44, v2
	v_mov_b32_e32 v45, v2
	v_mov_b32_e32 v46, v2
	v_mov_b32_e32 v47, v2
	v_mov_b32_e32 v48, v2
	v_mov_b32_e32 v49, v2
	v_mov_b32_e32 v50, v2
	v_mov_b32_e32 v51, v2
	v_mov_b32_e32 v52, v2
	v_mov_b32_e32 v53, v2
	v_mov_b32_e32 v54, v2
	v_mov_b32_e32 v55, v2
	v_mov_b32_e32 v56, v2
	v_mov_b32_e32 v57, v2
	v_mov_b32_e32 v58, v2
	v_mov_b32_e32 v59, v2
	v_mov_b32_e32 v60, v2
	v_mov_b32_e32 v61, v2
	v_mov_b32_e32 v62, v2
	v_mov_b32_e32 v63, v2
	v_mov_b32_e32 v64, v2
	v_mov_b32_e32 v65, v2
	v_mov_b32_e32 v66, v2
	v_mov_b32_e32 v67, v2
	v_mov_b32_e32 v68, v2
	v_mov_b32_e32 v69, v2
	v_mov_b32_e32 v70, v2
	v_mov_b32_e32 v71, v2
	v_mov_b32_e32 v72, v2
	v_mov_b32_e32 v73, v2
	v_mov_b32_e32 v74, v2
	v_mov_b32_e32 v75, v2
	v_mov_b32_e32 v76, v2
	v_mov_b32_e32 v77, v2
	v_mov_b32_e32 v78, v2
	v_mov_b32_e32 v79, v2
	v_mov_b32_e32 v80, v2
	v_mov_b32_e32 v81, v2
	v_mov_b32_e32 v82, v2
	v_mov_b32_e32 v83, v2
	v_mov_b32_e32 v84, v2
	v_mov_b32_e32 v85, v2
	v_mov_b32_e32 v86, v2
	v_mov_b32_e32 v87, v2
	v_mov_b32_e32 v88, v2
	v_mov_b32_e32 v89, v2
	v_mov_b32_e32 v90, v2
	v_mov_b32_e32 v91, v2
	v_mov_b32_e32 v92, v2
	v_mov_b32_e32 v93, v2
	v_mov_b32_e32 v94, v2
	v_mov_b32_e32 v95, v2
	v_mov_b32_e32 v96, v2
	v_mov_b32_e32 v97, v2
	v_mov_b32_e32 v98, v2
	v_mov_b32_e32 v99, v2
	v_mov_b32_e32 v100, v2
	v_mov_b32_e32 v101, v2
	v_mov_b32_e32 v102, v2
	v_mov_b32_e32 v103, v2
	v_mov_b32_e32 v104, v2
	v_mov_b32_e32 v105, v2
	v_mov_b32_e32 v106, v2
	v_mov_b32_e32 v107, v2
	v_mov_b32_e32 v108, v2
	v_mov_b32_e32 v109, v2
	v_mov_b32_e32 v110, v2
	v_mov_b32_e32 v111, v2
	v_mov_b32_e32 v112, v2
	v_mov_b32_e32 v113, v2
	v_mov_b32_e32 v114, v2
	v_mov_b32_e32 v115, v2
	v_mov_b32_e32 v116, v2
	v_mov_b32_e32 v117, v2
	v_mov_b32_e32 v118, v2
	v_mov_b32_e32 v119, v2
	v_mov_b32_e32 v120, v2
	v_mov_b32_e32 v121, v2
	v_mov_b32_e32 v122, v2
	v_mov_b32_e32 v123, v2
	v_mov_b32_e32 v124, v2
	v_mov_b32_e32 v125, v2
	v_mov_b32_e32 v126, v2
	v_mov_b32_e32 v127, v2
	v_mov_b32_e32 v128, v2
	v_mov_b32_e32 v129, v2
	s_add_i32 s62, s53, -2
	s_and_b32 s62, s62, 2
	s_mul_i32 s62, s62, 0x9000
	v_add_u32_e32 v0, s62, v164
	v_add_u32_e32 v165, s62, v163
	s_waitcnt lgkmcnt(0)
	s_barrier
	s_branch .LBB0_92

; #define MFMA32(a, b, c) __builtin_amdgcn_mfma_f32_32x32x16_bf16((a), (b), (c), 0, 0, 0)
; #define G_LOAD(KT) do { const int k0_ = (KT) << 6; _Pragma("unroll") for (int p = 0; p < 4; ++p) { \
;     ra[p] = *(const u32x4*)(ap + (size_t)(64 * p) * lda + k0_); rb[p] = *(const u32x4*)(bp + (size_t)(64 * p) * ldb + k0_); } } while (0)
; template <bool SWAP, bool SSQ, bool ZERO = true>
; DI void gemm_main(const u16* __restrict__ A, int lda, const u16* __restrict__ Bt, int ldb, int K, char* lds,
;                   f32x16 (&acc)[4][2], float* rs_lds) {
;     ...
;   for (int kt = 0; kt < nk; ++kt) {
;     const int st = (kt & 1) * 2 * G_TILE;
;     {
;       bf16x8 fa[2][4], fb[2][2];
; #pragma unroll
;       for (int i = 0; i < 4; ++i) fa[0][i] = *(const bf16x8*)(abase + st + i * 32 * GS);
; #pragma unroll
;       for (int i = 0; i < 2; ++i) fb[0][i] = *(const bf16x8*)(bbase + st + i * 32 * GS);
; #pragma unroll
;       for (int ks = 0; ks < 4; ++ks) {
;         if (ks + 1 < 4) {
; #pragma unroll
;           for (int i = 0; i < 4; ++i) fa[(ks + 1) & 1][i] = *(const bf16x8*)(abase + st + i * 32 * GS + (ks + 1) * 32);
; #pragma unroll
;           for (int i = 0; i < 2; ++i) fb[(ks + 1) & 1][i] = *(const bf16x8*)(bbase + st + i * 32 * GS + (ks + 1) * 32);
;         }
;         __builtin_amdgcn_sched_barrier(0);
;         __builtin_amdgcn_s_setprio(1);
; #pragma unroll
;         for (int mt = 0; mt < 4; ++mt)
; #pragma unroll
;           for (int nt = 0; nt < 2; ++nt)
;             acc[mt][nt] = SWAP ? MFMA32(fb[ks & 1][nt], fa[ks & 1][mt], acc[mt][nt]) : MFMA32(fa[ks & 1][mt], fb[ks & 1][nt], acc[mt][nt]);
;         __builtin_amdgcn_s_setprio(0);
;         __builtin_amdgcn_sched_barrier(0);
;       }
;     }
;     if (kt + 1 < nk) G_WRITE((kt + 1) & 1);
;     if (kt + 2 < nk) G_LOAD(kt + 2);
;     __syncthreads();
.LBB0_92:
	s_cmp_gt_u32 s52, 29
	s_cbranch_scc1 .Lg92_tail
	ds_read_b128 v[204:207], v165 offset:36864
	ds_read_b128 v[172:175], v0
	ds_read_b128 v[212:215], v165 offset:41472
	ds_read_b128 v[180:183], v0 offset:4608
	ds_read_b128 v[188:191], v0 offset:9216
	ds_read_b128 v[196:199], v0 offset:13824
	s_setprio 1
	s_waitcnt lgkmcnt(4)
	v_mfma_f32_32x32x16_bf16 v[114:129], v[204:207], v[172:175], v[114:129]
	ds_read_b128 v[208:211], v165 offset:36896
	s_waitcnt lgkmcnt(4)
	v_mfma_f32_32x32x16_bf16 v[98:113], v[212:215], v[172:175], v[98:113]
	ds_read_b128 v[176:179], v0 offset:32
	ds_read_b128 v[172:175], v0 offset:64
	s_waitcnt lgkmcnt(5)
	v_mfma_f32_32x32x16_bf16 v[82:97], v[204:207], v[180:183], v[82:97]
	ds_read_b128 v[216:219], v165 offset:41504
	v_mfma_f32_32x32x16_bf16 v[66:81], v[212:215], v[180:183], v[66:81]
	ds_read_b128 v[184:187], v0 offset:4640
	ds_read_b128 v[180:183], v0 offset:4672
	s_waitcnt lgkmcnt(7)
	v_mfma_f32_32x32x16_bf16 v[50:65], v[204:207], v[188:191], v[50:65]
	ds_read_b128 v[192:195], v0 offset:9248
	v_mfma_f32_32x32x16_bf16 v[34:49], v[212:215], v[188:191], v[34:49]
	ds_read_b128 v[200:203], v0 offset:13856
	ds_read_b128 v[188:191], v0 offset:9280
	s_waitcnt lgkmcnt(9)
	v_mfma_f32_32x32x16_bf16 v[18:33], v[204:207], v[196:199], v[18:33]
	ds_read_b128 v[204:207], v165 offset:36928
	v_mfma_f32_32x32x16_bf16 v[2:17], v[212:215], v[196:199], v[2:17]
	ds_read_b128 v[212:215], v165 offset:41536
	ds_read_b128 v[196:199], v0 offset:13888
	s_setprio 0
	s_setprio 1
	s_waitcnt lgkmcnt(10)
	v_mfma_f32_32x32x16_bf16 v[114:129], v[208:211], v[176:179], v[114:129]
	s_waitcnt lgkmcnt(8)
	v_mfma_f32_32x32x16_bf16 v[98:113], v[216:219], v[176:179], v[98:113]
	ds_read_b128 v[176:179], v0 offset:96
	s_waitcnt lgkmcnt(8)
	v_mfma_f32_32x32x16_bf16 v[82:97], v[208:211], v[184:187], v[82:97]
	v_mfma_f32_32x32x16_bf16 v[66:81], v[216:219], v[184:187], v[66:81]
	ds_read_b128 v[184:187], v0 offset:4704
	s_waitcnt lgkmcnt(7)
	v_mfma_f32_32x32x16_bf16 v[50:65], v[208:211], v[192:195], v[50:65]
	v_mfma_f32_32x32x16_bf16 v[34:49], v[216:219], v[192:195], v[34:49]
	ds_read_b128 v[192:195], v0 offset:9312
	s_waitcnt lgkmcnt(7)
	v_mfma_f32_32x32x16_bf16 v[18:33], v[208:211], v[200:203], v[18:33]
	ds_read_b128 v[208:211], v165 offset:36960
	v_mfma_f32_32x32x16_bf16 v[2:17], v[216:219], v[200:203], v[2:17]
	ds_read_b128 v[216:219], v165 offset:41568
	ds_read_b128 v[200:203], v0 offset:13920
	s_setprio 0
	s_setprio 1
	s_waitcnt lgkmcnt(8)
	v_mfma_f32_32x32x16_bf16 v[114:129], v[204:207], v[172:175], v[114:129]
	s_waitcnt lgkmcnt(7)
	v_mfma_f32_32x32x16_bf16 v[98:113], v[212:215], v[172:175], v[98:113]
	v_mfma_f32_32x32x16_bf16 v[82:97], v[204:207], v[180:183], v[82:97]
	v_mfma_f32_32x32x16_bf16 v[66:81], v[212:215], v[180:183], v[66:81]
	s_and_b32 s62, s53, 2
	s_mul_i32 s62, s62, 0x9000
	v_add_u32_e32 v240, s62, v162
	s_add_u32 s100, s40, s4
	s_addc_u32 s101, s41, s5
	s_add_u32 s100, s100, s86
	s_addc_u32 s101, s101, s87
	s_add_u32 s62, s14, s0
	s_addc_u32 s63, s15, s1
	s_add_u32 s62, s62, s86
	s_addc_u32 s63, s63, s87
	v_mfma_f32_32x32x16_bf16 v[50:65], v[204:207], v[188:191], v[50:65]
	s_waitcnt vmcnt(7)
	ds_write_b128 v240, v[130:133]
	global_load_dwordx4 v[130:133], v220, s[100:101] offset:256
	v_mfma_f32_32x32x16_bf16 v[34:49], v[212:215], v[188:191], v[34:49]
	s_waitcnt vmcnt(7)
	ds_write_b128 v240, v[134:137] offset:36864
	global_load_dwordx4 v[134:137], v220, s[62:63] offset:256
	s_waitcnt lgkmcnt(8)
	v_mfma_f32_32x32x16_bf16 v[18:33], v[204:207], v[196:199], v[18:33]
	s_waitcnt vmcnt(7)
	ds_write_b128 v240, v[138:141] offset:9216
	global_load_dwordx4 v[138:141], v221, s[100:101] offset:256
	v_mfma_f32_32x32x16_bf16 v[2:17], v[212:215], v[196:199], v[2:17]
	s_waitcnt vmcnt(7)
	ds_write_b128 v240, v[142:145] offset:46080
	global_load_dwordx4 v[142:145], v221, s[62:63] offset:256
	s_setprio 0
	s_setprio 1
	s_waitcnt lgkmcnt(6)
	v_mfma_f32_32x32x16_bf16 v[114:129], v[208:211], v[176:179], v[114:129]
	s_waitcnt vmcnt(7)
	ds_write_b128 v240, v[146:149] offset:18432
	global_load_dwordx4 v[146:149], v234, s[100:101] offset:256
	s_waitcnt lgkmcnt(6)
	v_mfma_f32_32x32x16_bf16 v[98:113], v[216:219], v[176:179], v[98:113]
	s_waitcnt vmcnt(7)
	ds_write_b128 v240, v[150:153] offset:55296
	global_load_dwordx4 v[150:153], v234, s[62:63] offset:256
	v_mfma_f32_32x32x16_bf16 v[82:97], v[208:211], v[184:187], v[82:97]
	s_waitcnt vmcnt(7)
	ds_write_b128 v240, v[154:157] offset:27648
	global_load_dwordx4 v[154:157], v235, s[100:101] offset:256
	v_mfma_f32_32x32x16_bf16 v[66:81], v[216:219], v[184:187], v[66:81]
	s_waitcnt vmcnt(7)
	ds_write_b128 v240, v[158:161] offset:64512
	global_load_dwordx4 v[158:161], v235, s[62:63] offset:256
	v_mfma_f32_32x32x16_bf16 v[50:65], v[208:211], v[192:195], v[50:65]
	v_mfma_f32_32x32x16_bf16 v[34:49], v[216:219], v[192:195], v[34:49]
	s_waitcnt lgkmcnt(8)
	v_mfma_f32_32x32x16_bf16 v[18:33], v[208:211], v[200:203], v[18:33]
	v_mfma_f32_32x32x16_bf16 v[2:17], v[216:219], v[200:203], v[2:17]
	s_setprio 0
	s_branch .LBB0_91
